# combo35: combo23 + barrier poll interval s_sleep 24 between polls of the arrival counter
# baseline (speedup 1.0000x reference)
; __device__ __forceinline__ unsigned xb_ld(unsigned* p)              { return __hip_atomic_load(p, __ATOMIC_RELAXED, __HIP_MEMORY_SCOPE_AGENT); }
; __device__ __forceinline__ unsigned xb_add(unsigned* p, unsigned v) { return __hip_atomic_fetch_add(p, v, __ATOMIC_RELAXED, __HIP_MEMORY_SCOPE_AGENT); }
; #define XB_SPIN(cond, bar) do { unsigned _sp = 0; while (cond) { __builtin_amdgcn_s_sleep(1); \
;     if ((++_sp & 255u) == 0u) { if (xb_ld(&(bar)[XB_TMO])) break; if (_sp > XB_SPIN_CAP) { atomicAdd(&(bar)[XB_TMO], 1u); break; } } } } while (0)
; __device__ __forceinline__ void xcd_barrier(const XcdBarrier& b) {
;     ...
;         const unsigned old = xb_add(&bar[XB_XSUB(bx)], 1u);
;         const unsigned gen = old / nloc;
;         if (old + 1u == (gen + 1u) * nloc) {
;             __builtin_amdgcn_fence(__ATOMIC_RELEASE, "agent");
;             asm volatile("s_waitcnt vmcnt(0)" ::: "memory");
;             const unsigned og = xb_add(&bar[XB_TOP], 1u);
;             const unsigned tg = og / nx;
;             if (og + 1u == (tg + 1u) * nx) xb_add(&bar[XB_TOPGEN], 1u);
;             else XB_SPIN(xb_ld(&bar[XB_TOPGEN]) == tg, bar);
;             __builtin_amdgcn_fence(__ATOMIC_ACQUIRE, "agent");
;             xb_add(&bar[XB_XGEN(bx)], 1u);
;             asm volatile("s_waitcnt vmcnt(0)" ::: "memory");
;         } else {
;             XB_SPIN(xb_ld(&bar[XB_XGEN(bx)]) == gen, bar);
;             __builtin_amdgcn_fence(__ATOMIC_ACQUIRE, "agent");
;             asm volatile("s_waitcnt vmcnt(0)" ::: "memory");
.Lxbg_spin:
	global_load_dword v16, v18, s[16:17] sc1
	s_waitcnt vmcnt(0)
	v_readfirstlane_b32 s12, v16
	s_cmp_ge_u32 s12, s20
	s_cbranch_scc1 .Lxbg_go
	s_sleep 24
	s_add_i32 s21, s21, 1
	s_cmp_lt_u32 s21, 0x40000
	s_cbranch_scc1 .Lxbg_spin

; __device__ __forceinline__ unsigned xb_ld(unsigned* p)              { return __hip_atomic_load(p, __ATOMIC_RELAXED, __HIP_MEMORY_SCOPE_AGENT); }
; __device__ __forceinline__ unsigned xb_add(unsigned* p, unsigned v) { return __hip_atomic_fetch_add(p, v, __ATOMIC_RELAXED, __HIP_MEMORY_SCOPE_AGENT); }
; #define XB_SPIN(cond, bar) do { unsigned _sp = 0; while (cond) { __builtin_amdgcn_s_sleep(1); \
;     if ((++_sp & 255u) == 0u) { if (xb_ld(&(bar)[XB_TMO])) break; if (_sp > XB_SPIN_CAP) { atomicAdd(&(bar)[XB_TMO], 1u); break; } } } } while (0)
; __device__ __forceinline__ void xcd_barrier(const XcdBarrier& b) {
;     ...
;         const unsigned old = xb_add(&bar[XB_XSUB(bx)], 1u);
;         const unsigned gen = old / nloc;
;         if (old + 1u == (gen + 1u) * nloc) {
;             __builtin_amdgcn_fence(__ATOMIC_RELEASE, "agent");
;             asm volatile("s_waitcnt vmcnt(0)" ::: "memory");
;             const unsigned og = xb_add(&bar[XB_TOP], 1u);
;             const unsigned tg = og / nx;
;             if (og + 1u == (tg + 1u) * nx) xb_add(&bar[XB_TOPGEN], 1u);
;             else XB_SPIN(xb_ld(&bar[XB_TOPGEN]) == tg, bar);
;             __builtin_amdgcn_fence(__ATOMIC_ACQUIRE, "agent");
;             xb_add(&bar[XB_XGEN(bx)], 1u);
;             asm volatile("s_waitcnt vmcnt(0)" ::: "memory");
;         } else {
;             XB_SPIN(xb_ld(&bar[XB_XGEN(bx)]) == gen, bar);
;             __builtin_amdgcn_fence(__ATOMIC_ACQUIRE, "agent");
;             asm volatile("s_waitcnt vmcnt(0)" ::: "memory");
.Lxbr_spin:
	global_load_dword v5, v10, s[16:17] sc1
	s_waitcnt vmcnt(0)
	v_readfirstlane_b32 s12, v5
	s_cmp_ge_u32 s12, s20
	s_cbranch_scc1 .Lxbr_go
	s_sleep 24
	s_add_i32 s21, s21, 1
	s_cmp_lt_u32 s21, 0x40000
	s_cbranch_scc1 .Lxbr_spin

; __device__ __forceinline__ unsigned xb_ld(unsigned* p)              { return __hip_atomic_load(p, __ATOMIC_RELAXED, __HIP_MEMORY_SCOPE_AGENT); }
; __device__ __forceinline__ unsigned xb_add(unsigned* p, unsigned v) { return __hip_atomic_fetch_add(p, v, __ATOMIC_RELAXED, __HIP_MEMORY_SCOPE_AGENT); }
; #define XB_SPIN(cond, bar) do { unsigned _sp = 0; while (cond) { __builtin_amdgcn_s_sleep(1); \
;     if ((++_sp & 255u) == 0u) { if (xb_ld(&(bar)[XB_TMO])) break; if (_sp > XB_SPIN_CAP) { atomicAdd(&(bar)[XB_TMO], 1u); break; } } } } while (0)
; __device__ __forceinline__ void xcd_barrier(const XcdBarrier& b) {
;     ...
;         const unsigned old = xb_add(&bar[XB_XSUB(bx)], 1u);
;         const unsigned gen = old / nloc;
;         if (old + 1u == (gen + 1u) * nloc) {
;             __builtin_amdgcn_fence(__ATOMIC_RELEASE, "agent");
;             asm volatile("s_waitcnt vmcnt(0)" ::: "memory");
;             const unsigned og = xb_add(&bar[XB_TOP], 1u);
;             const unsigned tg = og / nx;
;             if (og + 1u == (tg + 1u) * nx) xb_add(&bar[XB_TOPGEN], 1u);
;             else XB_SPIN(xb_ld(&bar[XB_TOPGEN]) == tg, bar);
;             __builtin_amdgcn_fence(__ATOMIC_ACQUIRE, "agent");
;             xb_add(&bar[XB_XGEN(bx)], 1u);
;             asm volatile("s_waitcnt vmcnt(0)" ::: "memory");
;         } else {
;             XB_SPIN(xb_ld(&bar[XB_XGEN(bx)]) == gen, bar);
;             __builtin_amdgcn_fence(__ATOMIC_ACQUIRE, "agent");
;             asm volatile("s_waitcnt vmcnt(0)" ::: "memory");
.Lxb0_spin:
	global_load_dword v5, v161, s[16:17] sc1
	s_waitcnt vmcnt(0)
	v_readfirstlane_b32 s12, v5
	s_cmp_ge_u32 s12, s2
	s_cbranch_scc1 .Lxb0_go
	s_sleep 24
	s_add_i32 s3, s3, 1
	s_cmp_lt_u32 s3, 0x40000
	s_cbranch_scc1 .Lxb0_spin
